# combined + softmax waves at static s_setprio 3 for the attention block
# speedup vs baseline: 1.0321x; 1.0321x over previous
; #define A2_WRITET(buf) do { char* kd_ = lds + L_K + (buf) * SHM_K; char* vd_ = lds + L_V + (buf) * 2 * SHM_V; \
;         *(bf16x8*)(kd_ + kws) = sk0; *(bf16x8*)(kd_ + kws + 32 * 256) = sk1; *(bf16x8*)(vd_ + vst0) = sv00; *(bf16x8*)(vd_ + vst1) = sv01; *(bf16x8*)(vd_ + SHM_V + vst0) = sv10; *(bf16x8*)(vd_ + SHM_V + vst1) = sv11; } while (0)
; __device__ __forceinline__ void attn2_block(const Blk& c, char* lds) {
;     ...
;     if (wid < 4) {
;         bf16x8 qr[8];
; #pragma unroll
;         for (int d0 = 0; d0 < 8; ++d0) qr[d0] = att::load8(c.Q + (size_t)(g * 32 + r32) * D + d0 * 16 + hi * 8);
;         asm volatile("s_waitcnt vmcnt(0)" ::: "memory"); A2_WRITET(0); __syncthreads();
;         const int qlo = c.P0 + g * 32, qm = qlo + r32 - 4 * hi;
;         const float* bt = (const float*)(lds + L_BT) + c.hm * 256;
;         float m_reg = -1e30f, l_reg = 0.f;
;         for (int s = 0; s <= NT; ++s) {
.LBB0_551:
	s_setprio 3
	s_or_b64 s[2:3], s[14:15], s[30:31]
	s_lshl_b32 s10, s82, 5
	s_lshl_b64 s[2:3], s[2:3], 8
	s_add_u32 s2, s27, s2
	v_or_b32_e32 v2, s10, v211
	s_addc_u32 s3, s34, s3
	v_lshlrev_b32_e32 v2, 8, v2
	v_lshl_add_u64 v[4:5], s[2:3], 0, v[2:3]
	v_mov_b32_e32 v217, v3
	v_lshl_add_u64 v[4:5], v[4:5], 0, v[216:217]
	global_load_dwordx4 v[104:107], v[4:5], off
	global_load_dwordx4 v[100:103], v[4:5], off offset:32
	global_load_dwordx4 v[96:99], v[4:5], off offset:64
	global_load_dwordx4 v[92:95], v[4:5], off offset:96
	global_load_dwordx4 v[88:91], v[4:5], off offset:128
	global_load_dwordx4 v[84:87], v[4:5], off offset:160
	global_load_dwordx4 v[80:83], v[4:5], off offset:192
	global_load_dwordx4 v[76:79], v[4:5], off offset:224
	s_or_b32 s85, s10, s30
	s_add_i32 s10, s30, s10
	s_waitcnt vmcnt(0)
	v_lshlrev_b32_e32 v4, 4, v211
	s_movk_i32 s2, 0x70
	s_lshl_b32 s11, s30, 8
	s_sub_i32 s10, s10, 27
	v_and_b32_e32 v5, 0x70, v4
	v_bitop3_b32 v121, v216, v4, s2 bitop3:0x78
	s_movk_i32 s2, 0x60
	v_lshlrev_b32_e32 v114, 2, v226
	s_and_b32 s11, s11, 0x1fc000
	v_add_u32_e32 v4, s10, v211
	v_mov_b32_e32 v215, v213
	v_add_u32_e32 v116, 0x10000, v229
	v_lshl_add_u32 v2, v211, 2, s17
	v_lshlrev_b32_e32 v119, 8, v211
	v_bitop3_b32 v122, v216, v5, 32 bitop3:0x36
	v_bitop3_b32 v123, v216, v5, 64 bitop3:0x36
	v_bitop3_b32 v124, v216, v5, s2 bitop3:0x36
	v_and_b32_e32 v126, 15, v211
	v_lshlrev_b32_e32 v126, 4, v126
	v_xor_b32_e32 v121, v216, v126
	v_xor_b32_e32 v122, 32, v121
	v_xor_b32_e32 v123, 64, v121
	v_xor_b32_e32 v124, 0x60, v121
	v_xor_b32_e32 v126, 0x80, v121
	v_xor_b32_e32 v127, 0x80, v122
	v_xor_b32_e32 v128, 0x80, v123
	v_xor_b32_e32 v129, 0x80, v124
	s_add_i32 s86, s85, 0xffffff80
	v_lshl_add_u32 v112, v225, 4, s16
	v_cmp_gt_u32_e64 s[2:3], 32, v225
	s_mov_b32 s84, 0
	v_cmp_eq_u32_e64 s[4:5], 0, v225
	s_add_u32 s87, s11, 0x4000
	v_sub_u32_e32 v125, v4, v114
	v_lshl_add_u64 v[108:109], s[46:47], 0, v[214:215]
	v_lshl_add_u64 v[110:111], s[58:59], 0, v[214:215]
	v_mov_b32_e32 v117, 0
	v_mov_b32_e32 v113, 0xf149f2ca
	s_mov_b64 s[82:83], 0
	s_mov_b32 s30, 0
	s_waitcnt lgkmcnt(0)
	s_barrier

; #define A2_WRITET(buf) do { char* kd_ = lds + L_K + (buf) * SHM_K; char* vd_ = lds + L_V + (buf) * 2 * SHM_V; \
;         *(bf16x8*)(kd_ + kws) = sk0; *(bf16x8*)(kd_ + kws + 32 * 256) = sk1; *(bf16x8*)(vd_ + vst0) = sv00; *(bf16x8*)(vd_ + vst1) = sv01; *(bf16x8*)(vd_ + SHM_V + vst0) = sv10; *(bf16x8*)(vd_ + SHM_V + vst1) = sv11; } while (0)
; __device__ __forceinline__ void attn2_block(const Blk& c, char* lds) {
;     ...
;             __syncthreads();
;             if (s + 1 < NT) { asm volatile("s_waitcnt vmcnt(0)" ::: "memory"); A2_WRITET((s + 1) & 1); }
;             __syncthreads();
;         }
;         if (hi == 0) LBb[r32] = l_reg;
;         __syncthreads();
.LBB0_630:
	s_or_b64 exec, exec, s[16:17]
	s_waitcnt lgkmcnt(0)
	s_waitcnt vmcnt(0)
	s_barrier
	s_barrier
	s_setprio 0
	s_and_saveexec_b64 s[4:5], s[2:3]
	s_cbranch_execz .LBB0_538
	v_add_f32_e32 v2, v4, v5
	v_fmac_f32_e32 v2, v115, v36
	v_lshl_add_u32 v4, v211, 2, s65
	ds_write_b32 v4, v2
	s_branch .LBB0_538
